# mixer role split: mixer body entered twice per layer; pass 1 waves 0-3 pool / waves 4-7 gating, pass 2 swapped, so each SIMD always pairs a streaming wave with a VALU/MFMA wave (v36 otherwise)
# baseline (speedup 1.0000x reference)
; #define tid  (fresh_tid_w(wave_s))
; __global__ void __launch_bounds__(512, 2) fwd_megakernel(Args a) {
;     ...
;         { const int w_ = wave;
;           const int pf = grouped ? grp * 1024 + gj * 32 + w_ * 4 : gw, pstep = grouped ? 1 : NGW, plim = grouped ? pf + 4 : (M / 128) * 16;
;           const int sf = grouped ? grp * 256 + gj * 8 + w_ : gw, sstep = grouped ? 1 : NGW, slim = grouped ? sf + 1 : (M / 128) * 4;
;           for (int rep = 0; rep < REP_MIX; ++rep) mixer_phase(lds, PROJ, YMIX, VSTAT, (const bf16*)(wl + W_POOL), a.in[I_POOLS] + l * 512, a.in[I_SGUG] + l * 512, (const bf16*)(wl + W_SGU), a.in[I_SGUB] + l * 512, pf, pstep, plim, sf, sstep, slim, tid); }
.LBB0_470:
	s_mov_b32 s99, 1
	v_readlane_b32 s0, v255, 25
	v_readlane_b32 s1, v255, 26
	s_andn2_b64 vcc, exec, s[0:1]
	s_cbranch_vccnz .LBB0_492
	s_mov_b32 s8, 0
	s_branch .LBB0_474

; #define LAS __attribute__((address_space(3)))
; #define tid  (fresh_tid_w(wave_s))
; #define lane (hw_lane())
; __device__ __forceinline__ void pool_load(const bf16* proj, int it, int lane, v4u (&raw)[12]) {
;     const int chunk = it >> 4, g = (it >> 2) & 3, rq = it & 3; proj += (size_t)(chunk >> 6) * GAP_P;
;     const size_t R0 = (size_t)chunk * 128 + rq * 32; const int tseq = (int)(R0 & (SEQ - 1)), r = lane & 15, q = lane >> 4;
; #pragma unroll
;     for (int i = 0; i < 12; ++i) { const int row = q + 4 * i; raw[i] = (v4u){0u, 0u, 0u, 0u};
;         if (row >= 16 || tseq != 0) raw[i] = __builtin_nontemporal_load((const v4u*)(proj + (R0 + row - 16) * DIN + g * 128 + r * 8)); }
; __device__ __forceinline__ void mixer_phase(LAS unsigned char* lds, const bf16* proj, bf16* ymix, const float* vstat, const bf16* WpT, const float* pscale, const float* sgu_g, const bf16* Wm, const float* sgu_b, int pool_first, int pool_step, int pool_limit, int sgu_first, int sgu_step, int sgu_limi ...
;     int tid = tid_in; asm volatile("" : "+v"(tid));
;     const int lane = tid & 63, wave = __builtin_amdgcn_readfirstlane(tid >> 6);
;     LAS unsigned char* wl = lds + wave * MIXW;
;     { v4u raw[12]; if (pool_first < pool_limit) pool_load(proj, pool_first, lane, raw);
;       for (int it = pool_first; it < pool_limit; it += pool_step) pool_item(wl, proj, ymix, WpT, pscale, it >> 4, (it >> 2) & 3, it & 3, lane, raw, it + pool_step < pool_limit ? it + pool_step : -1); }
.LBB0_492:
	s_mov_b64 s[26:27], s[58:59]
	s_mov_b64 s[20:21], s[58:59]
	s_mov_b64 s[38:39], s[58:59]
	v_mbcnt_lo_u32_b32 v0, -1, 0
	v_mbcnt_hi_u32_b32 v0, -1, v0
	s_nop 0
	v_or_b32_e32 v81, s93, v0
	s_nop 0
	s_nop 0
	v_readfirstlane_b32 s0, v81
	s_lshr_b32 s10, s0, 6
	s_lshr_b32 s98, s10, 2
	s_xor_b32 s98, s98, s99
	v_readlane_b32 s0, v254, 42
	v_and_b32_e32 v140, 63, v81
	s_mulk_i32 s10, 0x3300
	v_readlane_b32 s1, v254, 43
	s_add_i32 s2, s10, 0x100
	s_andn2_b64 vcc, exec, s[0:1]
	v_lshlrev_b32_e32 v83, 3, v140
	s_cbranch_vccnz .LBB0_508
	s_cmp_eq_u32 s98, 0
	s_cbranch_scc1 .LBB0_508
	s_add_u32 s9, s26, 0xf100000
	s_addc_u32 s12, s27, 0
	v_readlane_b32 s0, v255, 19
	v_readlane_b32 s6, v254, 46
	s_add_u32 s0, s9, s0
	v_readlane_b32 s1, v255, 18
	v_and_b32_e32 v0, 0x78, v83
	v_readlane_b32 s7, v254, 47
	s_addc_u32 s1, s12, s1
	v_lshrrev_b32_e32 v80, 4, v140
	s_andn2_b64 vcc, exec, s[6:7]
	s_mul_i32 s11, s5, 0xc00
	v_lshlrev_b32_e32 v192, 1, v0
	s_cbranch_vccnz .LBB0_495
	v_or_b32_e32 v4, s4, v80
	v_mov_b64_e32 v[0:1], s[0:1]
	s_movk_i32 s7, 0xc00
	v_mad_u64_u32 v[2:3], s[4:5], v4, s7, v[0:1]
	v_readlane_b32 s4, v254, 48
	v_add_u32_e32 v3, s11, v3
	s_lshl_b32 s86, s4, 1
	v_or_b32_e32 v4, 4, v4
	v_lshl_add_u64 v[2:3], v[2:3], 0, s[86:87]
	v_mad_u64_u32 v[0:1], s[4:5], v4, s7, v[0:1]
	v_lshl_add_u64 v[2:3], v[2:3], 0, v[192:193]
	v_add_u32_e32 v1, s11, v1
	v_add_co_u32_e32 v2, vcc, s83, v2
	v_lshl_add_u64 v[0:1], v[0:1], 0, s[86:87]
	s_nop 0
	v_addc_co_u32_e32 v3, vcc, -1, v3, vcc
	v_lshl_add_u64 v[0:1], v[0:1], 0, v[192:193]
	v_add_co_u32_e32 v4, vcc, 0xffff4000, v0
	s_nop 1
	v_addc_co_u32_e32 v5, vcc, -1, v1, vcc
	global_load_dwordx4 v[0:3], v[2:3], off nt
	s_nop 0
	global_load_dwordx4 v[4:7], v[4:5], off nt
	s_branch .LBB0_496

; #define LAS __attribute__((address_space(3)))
; #define LDS_WAIT() asm volatile("s_waitcnt lgkmcnt(0)" ::: "memory")
; #define lane (hw_lane())
; __device__ __forceinline__ void sgu_item(LAS unsigned char* wl, const bf16* proj, bf16* ymix, const float* vstat, const float* sgu_g, const bf16* Wm, const float* sgu_b, int chunk, int h, int lane) {
;     proj += (size_t)(chunk >> 6) * GAP_P; ymix += (size_t)(chunk >> 6) * GAP_Y;
;     typedef float f32x2 __attribute__((ext_vector_type(2)));
;     const size_t R0 = (size_t)chunk * 128;
;     const int r = lane & 15, q = lane >> 4, c16 = lane & 3, rsub = lane >> 2;
;     LAS f32x2* st = (LAS f32x2*)(wl + 128 * VP2);
; #pragma unroll
;     for (int hh = 0; hh < 2; ++hh) { const f32x4* sp = (const f32x4*)(vstat + (R0 + lane + 64 * hh) * 16);
;         const f32x4 a = sp[0], b = sp[1], c = sp[2], d = sp[3];
;         const float s1 = ((a[0] + a[2]) + (b[0] + b[2])) + ((c[0] + c[2]) + (d[0] + d[2])), s2 = ((a[1] + a[3]) + (b[1] + b[3])) + ((c[1] + c[3]) + (d[1] + d[3]));
;         const float mean = s1 * (1.0f / 512.0f), var = fmaxf(s2 * (1.0f / 512.0f) - mean * mean, 0.f);
;         st[lane + 64 * hh] = (f32x2){mean, __builtin_amdgcn_rsqf(var + EPS)}; }
;     bf16x8 wmf[20];
;     { const bf16* wm = Wm + (size_t)(h * 128 + r) * 128 + q * 8; int f = 0;
; #pragma unroll
;       for (int ks = 0; ks < 4; ++ks)
; #pragma unroll
;         for (int tb = 2 * ks; tb < 8; ++tb) wmf[f++] = *(const bf16x8*)(wm + (size_t)(16 * tb) * 128 + ks * 32); }
;     float bias[8];
; #pragma unroll
;     for (int tb = 0; tb < 8; ++tb) bias[tb] = sgu_b[h * 128 + 16 * tb + r];
;     LDS_WAIT();
; __device__ __forceinline__ void mixer_phase(LAS unsigned char* lds, const bf16* proj, bf16* ymix, const float* vstat, const bf16* WpT, const float* pscale, const float* sgu_g, const bf16* Wm, const float* sgu_b, int pool_first, int pool_step, int pool_limit, int sgu_first, int sgu_step, int sgu_limi ...
;     ...
;     for (int j = sgu_first; j < sgu_limit; j += sgu_step) sgu_item(wl, proj, ymix, vstat, sgu_g, Wm, sgu_b, j >> 2, j & 3, lane);
.LBB0_508:
	v_readlane_b32 s0, v254, 50
	v_readlane_b32 s1, v254, 51
	s_andn2_b64 vcc, exec, s[0:1]
	s_cbranch_vccnz .LBB0_513
	s_cmp_lg_u32 s98, 0
	s_cbranch_scc1 .LBB0_513
	v_readlane_b32 s22, v255, 37
	s_lshl_b32 s86, s22, 9
	v_readlane_b32 s4, v253, 3
	s_lshl_b64 s[0:1], s[86:87], 2
	v_readlane_b32 s14, v253, 13
	v_readlane_b32 s5, v253, 4
	v_readlane_b32 s15, v253, 14
	s_add_u32 s14, s4, s0
	s_waitcnt vmcnt(0)
	v_lshrrev_b32_e32 v0, 1, v81
	v_readlane_b32 s18, v253, 17
	s_addc_u32 s15, s5, s1
	v_and_b32_e32 v2, 24, v0
	v_readlane_b32 s0, v255, 39
	v_readlane_b32 s19, v253, 18
	s_add_u32 s18, s38, 0x25100000
	v_lshlrev_b32_e32 v192, 1, v2
	v_readlane_b32 s1, v255, 40
	s_addc_u32 s19, s39, 0
	v_or_b32_e32 v7, 0x70, v140
	v_lshl_add_u64 v[0:1], s[0:1], 0, v[192:193]
	s_mov_b64 s[0:1], 0x1e40000
	v_lshl_add_u64 v[144:145], v[0:1], 0, s[0:1]
	s_add_u32 s0, s20, 0x10900400
	v_and_b32_e32 v8, 48, v81
	v_and_b32_e32 v143, 15, v81
	v_and_b32_e32 v0, 24, v83
	s_addc_u32 s1, s21, 0
	v_lshl_or_b32 v192, v7, 11, v8
	v_add_u32_e32 v4, s2, v0
	v_bfe_u32 v0, v81, 2, 2
	v_or_b32_e32 v6, 48, v140
	v_lshl_add_u64 v[146:147], s[0:1], 0, v[192:193]
	v_lshl_or_b32 v192, v143, 11, v8
	v_or_b32_e32 v0, v0, v2
	v_lshl_add_u64 v[148:149], s[20:21], 0, v[192:193]
	v_lshl_or_b32 v192, v6, 11, v8
	v_mul_u32_u24_e32 v2, 0x50, v0
	v_lshl_add_u64 v[150:151], s[0:1], 0, v[192:193]
	s_add_u32 s0, s26, 0xf100400
	v_mul_u32_u24_e32 v0, 0xc00, v7
	s_addc_u32 s1, s27, 0
	v_mul_hi_u32_u24_e32 v1, 0xc00, v7
	v_or_b32_e32 v0, v0, v8
	v_lshl_add_u64 v[152:153], s[0:1], 0, v[0:1]
	v_mul_u32_u24_e32 v0, 0xc00, v143
	v_mul_hi_u32_u24_e32 v1, 0xc00, v143
	v_or_b32_e32 v0, v0, v8
	v_lshl_add_u64 v[154:155], s[26:27], 0, v[0:1]
	v_mul_u32_u24_e32 v0, 0xc00, v6
	v_readlane_b32 s23, v255, 38
	v_lshrrev_b32_e32 v3, 2, v140
	v_mul_hi_u32_u24_e32 v1, 0xc00, v6
	v_or_b32_e32 v0, v0, v8
	v_add_u32_e32 v141, s2, v83
	v_lshl_add_u32 v218, v3, 3, s2
	v_lshl_add_u64 v[156:157], s[0:1], 0, v[0:1]
	s_lshl_b64 s[0:1], s[22:23], 11
	v_readlane_b32 s2, v255, 14
	v_mul_u32_u24_e32 v5, 0x50, v3
	v_mul_hi_u32_u24_e32 v1, 0xc00, v3
	v_mul_u32_u24_e32 v0, 0xc00, v3
	v_and_b32_e32 v3, 3, v81
	s_add_u32 s0, s2, s0
	v_readlane_b32 s2, v255, 15
	v_readlane_b32 s7, v253, 6
	v_lshl_or_b32 v0, v3, 4, v0
	v_lshlrev_b32_e32 v192, 5, v3
	s_addc_u32 s1, s2, s1
	v_or_b32_e32 v142, 64, v140
	v_lshl_add_u64 v[158:159], s[26:27], 0, v[0:1]
	v_lshl_add_u64 v[160:161], s[0:1], 0, v[192:193]
	v_add_u32_e32 v219, v4, v5
	v_add_u32_e32 v220, v4, v2
	v_readlane_b32 s4, v254, 62
	v_readlane_b32 s5, v254, 61
	v_readlane_b32 s2, v254, 49
	v_readlane_b32 s7, v254, 63
	v_readlane_b32 s6, v253, 5
	v_readlane_b32 s8, v253, 7
	v_readlane_b32 s9, v253, 8
	v_readlane_b32 s10, v253, 9
	v_readlane_b32 s11, v253, 10
	v_readlane_b32 s12, v253, 11
	v_readlane_b32 s13, v253, 12
	v_readlane_b32 s16, v253, 15
	v_readlane_b32 s17, v253, 16

; #define lane (hw_lane())
; __device__ __forceinline__ void mixer_phase(LAS unsigned char* lds, const bf16* proj, bf16* ymix, const float* vstat, const bf16* WpT, const float* pscale, const float* sgu_g, const bf16* Wm, const float* sgu_b, int pool_first, int pool_step, int pool_limit, int sgu_first, int sgu_step, int sgu_limi ...
;     ...
;     { v4u raw[12]; if (pool_first < pool_limit) pool_load(proj, pool_first, lane, raw);
;       for (int it = pool_first; it < pool_limit; it += pool_step) pool_item(wl, proj, ymix, WpT, pscale, it >> 4, (it >> 2) & 3, it & 3, lane, raw, it + pool_step < pool_limit ? it + pool_step : -1); }
;     for (int j = sgu_first; j < sgu_limit; j += sgu_step) sgu_item(wl, proj, ymix, vstat, sgu_g, Wm, sgu_b, j >> 2, j & 3, lane);
.LBB0_513:
	s_cmp_eq_u32 s99, 0
	s_cbranch_scc1 .Lmix_done
	s_mov_b32 s99, 0
	s_waitcnt lgkmcnt(0)
	s_branch .LBB0_491
